# gather: static priority raise for waves 4..7 on top of the XCD-local seams
# speedup vs baseline: 1.0027x; 1.0003x over previous
.LBB0_594:
	s_cmp_lt_i32 s56, 8
	s_cselect_b64 s[0:1], -1, 0
	s_and_b64 s[0:1], s[0:1], s[4:5]
	s_andn2_b64 vcc, exec, s[0:1]
	s_cbranch_vccnz .LBB0_619
	s_cmpk_gt_i32 s33, 0x7ff
	v_mbcnt_lo_u32_b32 v0, -1, 0
	v_mbcnt_hi_u32_b32 v0, -1, v0
	s_cbranch_scc1 .LBB0_619
	v_readlane_b32 s64, v248, 0
	s_lshr_b32 s64, s64, 6
	s_cmp_ge_u32 s64, 4
	s_cbranch_scc0 .LpgL0_noprio
	s_setprio 1
.LpgL0_noprio:
	s_and_b32 s63, s2, 7
	s_lshl_b32 s63, s63, 8
	s_lshr_b32 s64, s2, 3
	s_lshl_b32 s64, s64, 3
	s_or_b32 s63, s63, s64
	s_and_b32 s64, s33, 7
	s_or_b32 s63, s63, s64

.LBB0_1075:
	s_cmp_lt_i32 s56, 16
	s_cselect_b64 s[0:1], -1, 0
	s_and_b64 s[0:1], s[0:1], s[4:5]
	s_andn2_b64 vcc, exec, s[0:1]
	s_cbranch_vccnz .LBB0_1083
	s_cmpk_gt_i32 s33, 0x7ff
	v_mbcnt_lo_u32_b32 v0, -1, 0
	v_mbcnt_hi_u32_b32 v0, -1, v0
	s_cbranch_scc1 .LBB0_1083
	v_readlane_b32 s64, v248, 0
	s_lshr_b32 s64, s64, 6
	s_cmp_ge_u32 s64, 4
	s_cbranch_scc0 .LpgL1_noprio
	s_setprio 1
